# software-pipelined the HGRN2 chunk-scan loop (hgB): next four chunks' UT/DEC loads prefetched with a counted vmcnt(8) instead of a vmcnt(0) drain per chunk; plus the earlier setprio/final-barrier edit
# speedup vs baseline: 1.0105x; 1.0009x over previous
; __device__ __forceinline__ int opaque_tid() { int t = threadIdx.x; asm volatile("" : "+v"(t)); return t; }
; DI unsigned pk2(float lo, float hi) { return pg8::cvt_pk_bf16(lo, hi); }
; DI void hg_phase_b(const float* UT, const float* DEC, bf16_t* ST) {
;     for (int idx = blockIdx.x * 512 + opaque_tid(); idx < 32 * 4096; idx += gridDim.x * 512) {
;         const int bh = idx >> 12, rem = idx & 4095, dv = rem >> 5, dk4 = (rem & 31) * 4;
;         f32x4 st = {0.f, 0.f, 0.f, 0.f};
; #pragma unroll 4
;         for (int n = 0; n < 64; ++n) {
;             const size_t ch = (size_t)bh * 64 + n;
;             u32x2 w; w.x = pk2(st.x, st.y); w.y = pk2(st.z, st.w);
;             *(u32x2*)(ST + ch * 16384 + dv * 128 + dk4) = w;
;             const f32x4 u = *(const f32x4*)(UT + ch * 16384 + dv * 128 + dk4), dc = *(const f32x4*)(DEC + ch * 128 + dk4);
;             st = dc * st + u;
;         }
;     }
; }
.LBB0_341:
	s_or_b64 exec, exec, s[4:5]
	s_mov_b64 s[6:7], s[0:1]
	s_waitcnt lgkmcnt(0)
	v_mov_b32_e32 v0, v220
	v_readlane_b32 s4, v253, 3
	s_barrier
	s_nop 0
	v_add_u32_e32 v10, s4, v0
	s_mov_b32 s4, 0x20000
	v_cmp_gt_i32_e32 vcc, s4, v10
	s_and_saveexec_b64 s[4:5], vcc
	s_cbranch_execz .LBB0_346
	s_load_dwordx2 s[6:7], s[6:7], 0xb0
	v_lshlrev_b32_e32 v0, 2, v0
	v_lshl_add_u32 v11, s2, 11, v0
	s_lshl_b32 s16, s86, 11
	s_mov_b64 s[8:9], 0
	s_mov_b32 s26, 0x1ffff
	s_waitcnt lgkmcnt(0)
	s_add_u32 s10, s6, 0x19600000
	s_addc_u32 s11, s7, 0
	s_add_u32 s12, s6, 0x19610000
	s_addc_u32 s13, s7, 0
	s_add_u32 s14, s6, 0x19620000
	s_addc_u32 s15, s7, 0
	s_add_u32 s18, s6, 0x19630000
	s_addc_u32 s19, s7, 0
	s_add_u32 s20, s6, 0x700000
	s_addc_u32 s21, s7, 0
	s_add_u32 s22, s6, 0x23600000
	s_addc_u32 s23, s7, 0
	s_add_u32 s24, s6, 0x23608000
	s_addc_u32 s25, s7, 0
	s_add_u32 s98, s6, 0x23610000
	s_addc_u32 s99, s7, 0
	s_add_u32 s100, s6, 0x23618000
	s_addc_u32 s101, s7, 0
.LBB0_343:
	v_lshlrev_b32_e32 v0, 2, v11
	v_ashrrev_i32_e32 v4, 12, v10
	v_and_b32_e32 v6, 0x1f0, v0
	v_and_b32_e32 v7, 0xfe00, v0
	v_lshlrev_b32_e32 v0, 1, v11
	v_ashrrev_i32_e32 v5, 31, v4
	v_and_b32_e32 v8, 0x7f00, v0
	v_and_b32_e32 v9, 0xf8, v0
	v_lshlrev_b64 v[0:1], 15, v[4:5]
	v_lshlrev_b64 v[2:3], 22, v[4:5]
	v_or_b32_e32 v0, v0, v6
	v_or3_b32 v2, v2, v7, v6
	v_lshlrev_b64 v[4:5], 21, v[4:5]
	v_mov_b32_e32 v6, 0
	v_or3_b32 v4, v4, v8, v9
	s_mov_b32 s27, 16
	v_mov_b32_e32 v7, v6
	v_mov_b32_e32 v8, v6
	v_mov_b32_e32 v9, v6
	global_load_dwordx4 v[32:35], v2, s[10:11]
	global_load_dwordx4 v[48:51], v0, s[20:21]
	global_load_dwordx4 v[36:39], v2, s[12:13]
	global_load_dwordx4 v[52:55], v0, s[20:21] offset:512
	global_load_dwordx4 v[40:43], v2, s[14:15]
	global_load_dwordx4 v[56:59], v0, s[20:21] offset:1024
	global_load_dwordx4 v[44:47], v2, s[18:19]
	global_load_dwordx4 v[60:63], v0, s[20:21] offset:1536
	v_add_u32_e32 v2, 0x40000, v2
	v_add_u32_e32 v0, 0x800, v0
.Lhgb_loop:
	global_load_dwordx4 v[64:67], v2, s[10:11]
	global_load_dwordx4 v[80:83], v0, s[20:21]
	global_load_dwordx4 v[68:71], v2, s[12:13]
	global_load_dwordx4 v[84:87], v0, s[20:21] offset:512
	global_load_dwordx4 v[72:75], v2, s[14:15]
	global_load_dwordx4 v[88:91], v0, s[20:21] offset:1024
	global_load_dwordx4 v[76:79], v2, s[18:19]
	global_load_dwordx4 v[92:95], v0, s[20:21] offset:1536
	v_add_u32_e32 v2, 0x40000, v2
	v_add_u32_e32 v0, 0x800, v0
	s_waitcnt vmcnt(8)
	v_cvt_pk_bf16_f32 v12, v6, v7
	v_cvt_pk_bf16_f32 v13, v8, v9
	global_store_dwordx2 v4, v[12:13], s[22:23]
	v_pk_fma_f32 v[6:7], v[6:7], v[48:49], v[32:33]
	v_pk_fma_f32 v[8:9], v[8:9], v[50:51], v[34:35]
	v_cvt_pk_bf16_f32 v14, v6, v7
	v_cvt_pk_bf16_f32 v15, v8, v9
	global_store_dwordx2 v4, v[14:15], s[24:25]
	v_pk_fma_f32 v[6:7], v[6:7], v[52:53], v[36:37]
	v_pk_fma_f32 v[8:9], v[8:9], v[54:55], v[38:39]
	v_cvt_pk_bf16_f32 v16, v6, v7
	v_cvt_pk_bf16_f32 v17, v8, v9
	global_store_dwordx2 v4, v[16:17], s[98:99]
	v_pk_fma_f32 v[6:7], v[6:7], v[56:57], v[40:41]
	v_pk_fma_f32 v[8:9], v[8:9], v[58:59], v[42:43]
	v_cvt_pk_bf16_f32 v18, v6, v7
	v_cvt_pk_bf16_f32 v19, v8, v9
	global_store_dwordx2 v4, v[18:19], s[100:101]
	v_pk_fma_f32 v[6:7], v[6:7], v[60:61], v[44:45]
	v_pk_fma_f32 v[8:9], v[8:9], v[62:63], v[46:47]
	v_add_u32_e32 v4, 0x20000, v4
	s_sub_u32 s27, s27, 2
	s_cmp_eq_u32 s27, 0
	s_cbranch_scc1 .Lhgb_last
	global_load_dwordx4 v[32:35], v2, s[10:11]
	global_load_dwordx4 v[48:51], v0, s[20:21]
	global_load_dwordx4 v[36:39], v2, s[12:13]
	global_load_dwordx4 v[52:55], v0, s[20:21] offset:512
	global_load_dwordx4 v[40:43], v2, s[14:15]
	global_load_dwordx4 v[56:59], v0, s[20:21] offset:1024
	global_load_dwordx4 v[44:47], v2, s[18:19]
	global_load_dwordx4 v[60:63], v0, s[20:21] offset:1536
	v_add_u32_e32 v2, 0x40000, v2
	v_add_u32_e32 v0, 0x800, v0
	s_waitcnt vmcnt(8)
	v_cvt_pk_bf16_f32 v12, v6, v7
	v_cvt_pk_bf16_f32 v13, v8, v9
	global_store_dwordx2 v4, v[12:13], s[22:23]
	v_pk_fma_f32 v[6:7], v[6:7], v[80:81], v[64:65]
	v_pk_fma_f32 v[8:9], v[8:9], v[82:83], v[66:67]
	v_cvt_pk_bf16_f32 v14, v6, v7
	v_cvt_pk_bf16_f32 v15, v8, v9
	global_store_dwordx2 v4, v[14:15], s[24:25]
	v_pk_fma_f32 v[6:7], v[6:7], v[84:85], v[68:69]
	v_pk_fma_f32 v[8:9], v[8:9], v[86:87], v[70:71]
	v_cvt_pk_bf16_f32 v16, v6, v7
	v_cvt_pk_bf16_f32 v17, v8, v9
	global_store_dwordx2 v4, v[16:17], s[98:99]
	v_pk_fma_f32 v[6:7], v[6:7], v[88:89], v[72:73]
	v_pk_fma_f32 v[8:9], v[8:9], v[90:91], v[74:75]
	v_cvt_pk_bf16_f32 v18, v6, v7
	v_cvt_pk_bf16_f32 v19, v8, v9
	global_store_dwordx2 v4, v[18:19], s[100:101]
	v_pk_fma_f32 v[6:7], v[6:7], v[92:93], v[76:77]
	v_pk_fma_f32 v[8:9], v[8:9], v[94:95], v[78:79]
	v_add_u32_e32 v4, 0x20000, v4
	s_branch .Lhgb_loop
.Lhgb_last:
	s_waitcnt vmcnt(0)
	v_cvt_pk_bf16_f32 v12, v6, v7
	v_cvt_pk_bf16_f32 v13, v8, v9
	global_store_dwordx2 v4, v[12:13], s[22:23]
	v_pk_fma_f32 v[6:7], v[6:7], v[80:81], v[64:65]
	v_pk_fma_f32 v[8:9], v[8:9], v[82:83], v[66:67]
	v_cvt_pk_bf16_f32 v14, v6, v7
	v_cvt_pk_bf16_f32 v15, v8, v9
	global_store_dwordx2 v4, v[14:15], s[24:25]
	v_pk_fma_f32 v[6:7], v[6:7], v[84:85], v[68:69]
	v_pk_fma_f32 v[8:9], v[8:9], v[86:87], v[70:71]
	v_cvt_pk_bf16_f32 v16, v6, v7
	v_cvt_pk_bf16_f32 v17, v8, v9
	global_store_dwordx2 v4, v[16:17], s[98:99]
	v_pk_fma_f32 v[6:7], v[6:7], v[88:89], v[72:73]
	v_pk_fma_f32 v[8:9], v[8:9], v[90:91], v[74:75]
	v_cvt_pk_bf16_f32 v18, v6, v7
	v_cvt_pk_bf16_f32 v19, v8, v9
	global_store_dwordx2 v4, v[18:19], s[100:101]
	v_pk_fma_f32 v[6:7], v[6:7], v[92:93], v[76:77]
	v_pk_fma_f32 v[8:9], v[8:9], v[94:95], v[78:79]
	v_add_u32_e32 v4, 0x20000, v4
	v_add_u32_e32 v10, s74, v10
	v_cmp_lt_i32_e32 vcc, s26, v10
	s_or_b64 s[8:9], vcc, s[8:9]
	v_add_u32_e32 v11, s16, v11
	s_andn2_b64 exec, exec, s[8:9]
	s_cbranch_execnz .LBB0_343

; __global__ void __launch_bounds__(512, 2) fwd_megakernel(P p_arg) {
	.amdhsa_kernel _Z14fwd_megakernel1P
		.amdhsa_group_segment_fixed_size 0
		.amdhsa_private_segment_fixed_size 0
		.amdhsa_kernarg_size 440
		.amdhsa_user_sgpr_count 2
		.amdhsa_user_sgpr_dispatch_ptr 0
		.amdhsa_user_sgpr_queue_ptr 0
		.amdhsa_user_sgpr_kernarg_segment_ptr 1
		.amdhsa_user_sgpr_dispatch_id 0
		.amdhsa_user_sgpr_kernarg_preload_length 0
		.amdhsa_user_sgpr_kernarg_preload_offset 0
		.amdhsa_user_sgpr_private_segment_size 0
		.amdhsa_uses_dynamic_stack 0
		.amdhsa_enable_private_segment 0
		.amdhsa_system_sgpr_workgroup_id_x 1
		.amdhsa_system_sgpr_workgroup_id_y 0
		.amdhsa_system_sgpr_workgroup_id_z 0
		.amdhsa_system_sgpr_workgroup_info 0
		.amdhsa_system_vgpr_workitem_id 2
		.amdhsa_next_free_vgpr 254
		.amdhsa_next_free_sgpr 102
		.amdhsa_accum_offset 256
		.amdhsa_reserve_vcc 1
		.amdhsa_float_round_mode_32 0
		.amdhsa_float_round_mode_16_64 0
		.amdhsa_float_denorm_mode_32 3
		.amdhsa_float_denorm_mode_16_64 3
		.amdhsa_dx10_clamp 1
		.amdhsa_ieee_mode 1
		.amdhsa_fp16_overflow 0
		.amdhsa_tg_split 0
		.amdhsa_exception_fp_ieee_invalid_op 0
		.amdhsa_exception_fp_denorm_src 0
		.amdhsa_exception_fp_ieee_div_zero 0
		.amdhsa_exception_fp_ieee_overflow 0
		.amdhsa_exception_fp_ieee_underflow 0
		.amdhsa_exception_fp_ieee_inexact 0
		.amdhsa_exception_int_div_zero 0
	.end_amdhsa_kernel

; __global__ void __launch_bounds__(512, 2) fwd_megakernel(P p_arg) {
amdhsa.kernels:
  - .agpr_count:     0
    .args:
      - .offset:         0
        .size:           184
        .value_kind:     by_value
      - .offset:         184
        .size:           4
        .value_kind:     hidden_block_count_x
      - .offset:         188
        .size:           4
        .value_kind:     hidden_block_count_y
      - .offset:         192
        .size:           4
        .value_kind:     hidden_block_count_z
      - .offset:         196
        .size:           2
        .value_kind:     hidden_group_size_x
      - .offset:         198
        .size:           2
        .value_kind:     hidden_group_size_y
      - .offset:         200
        .size:           2
        .value_kind:     hidden_group_size_z
      - .offset:         202
        .size:           2
        .value_kind:     hidden_remainder_x
      - .offset:         204
        .size:           2
        .value_kind:     hidden_remainder_y
      - .offset:         206
        .size:           2
        .value_kind:     hidden_remainder_z
      - .offset:         224
        .size:           8
        .value_kind:     hidden_global_offset_x
      - .offset:         232
        .size:           8
        .value_kind:     hidden_global_offset_y
      - .offset:         240
        .size:           8
        .value_kind:     hidden_global_offset_z
      - .offset:         248
        .size:           2
        .value_kind:     hidden_grid_dims
      - .offset:         272
        .size:           8
        .value_kind:     hidden_multigrid_sync_arg
      - .offset:         304
        .size:           4
        .value_kind:     hidden_dynamic_lds_size
    .group_segment_fixed_size: 0
    .kernarg_segment_align: 8
    .kernarg_segment_size: 440
    .language:       OpenCL C
    .language_version:
      - 2
      - 0
    .max_flat_workgroup_size: 512
    .name:           _Z14fwd_megakernel1P
    .private_segment_fixed_size: 0
    .sgpr_count:     108
    .sgpr_spill_count: 15
    .symbol:         _Z14fwd_megakernel1P.kd
    .uniform_work_group_size: 1
    .uses_dynamic_stack: false
    .vgpr_count:     254
    .vgpr_spill_count: 0
    .wavefront_size: 64
